# scan waves: unmasked output stores (all lanes of a quad/oct hold the identical value), removes saveexec+branch per step
# speedup vs baseline: 1.0221x; 1.0096x over previous
.LBB0_859:
	s_waitcnt lgkmcnt(0)
	v_mov_b32_e32 v95, v96
	v_add_u32_e32 v96, s7, v100
	ds_read_b128 v[70:73], v96 offset:1568
	ds_read_b128 v[66:69], v96 offset:1584
	ds_read_b128 v[50:53], v96 offset:1824
	ds_read_b128 v[46:49], v96 offset:1840
	ds_read_b128 v[54:57], v96 offset:2080
	ds_read_b128 v[42:45], v96 offset:2096
	ds_read_b128 v[78:81], v96 offset:2336
	ds_read_b128 v[74:77], v96 offset:2352
	ds_read_b128 v[62:65], v96 offset:2592
	ds_read_b128 v[58:61], v96 offset:2608
	v_pk_fma_f32 v[34:35], v[84:85], v[34:35], 0 op_sel_hi:[1,1,0]
	v_pk_fma_f32 v[22:23], v[84:85], v[22:23], 0 op_sel_hi:[1,1,0]
	v_pk_fma_f32 v[34:35], v[86:87], v[36:37], v[34:35]
	v_pk_fma_f32 v[22:23], v[86:87], v[24:25], v[22:23]
	v_add_u32_e32 v103, s7, v102
	v_mov_b32_e32 v98, s7
	v_pk_fma_f32 v[24:25], v[88:89], v[38:39], v[34:35]
	v_pk_fma_f32 v[18:19], v[88:89], v[18:19], v[22:23]
	ds_read_b32 v0, v103 offset:2848
	ds_read_b64 v[98:99], v98 offset:3104
	v_pk_fma_f32 v[22:23], v[90:91], v[40:41], v[24:25]
	v_pk_fma_f32 v[20:21], v[90:91], v[20:21], v[18:19]
	v_add_f32_e32 v18, v22, v23
	v_add_f32_e32 v19, v20, v21
	s_nop 0
	v_add_f32_dpp v18, v18, v18 quad_perm:[1,0,3,2] row_mask:0xf bank_mask:0xf bound_ctrl:1
	v_add_f32_dpp v19, v19, v19 quad_perm:[1,0,3,2] row_mask:0xf bank_mask:0xf bound_ctrl:1
	s_nop 0
	v_add_f32_dpp v18, v18, v18 quad_perm:[2,3,0,1] row_mask:0xf bank_mask:0xf bound_ctrl:1
	v_add_f32_dpp v19, v19, v19 quad_perm:[2,3,0,1] row_mask:0xf bank_mask:0xf bound_ctrl:1
	s_nop 0
	v_add_f32_dpp v18, v18, v18 row_half_mirror row_mask:0xf bank_mask:0xf bound_ctrl:1
	v_mov_b32_dpp v20, v19 row_half_mirror row_mask:0xf bank_mask:0xf bound_ctrl:1
	v_mov_b32_e32 v22, v97
	v_mov_b32_e32 v23, v18
	v_pk_mul_f32 v[22:23], v[22:23], v[94:95]
	v_add_f32_e32 v19, v19, v20
	v_add_f32_e32 v19, v23, v19
	v_add_f32_e32 v19, v22, v19
	s_ashr_i32 s47, s46, 31
	v_bfe_u32 v20, v19, 16, 1
	s_lshl_b64 s[20:21], s[46:47], 9
	v_add3_u32 v19, v19, v20, s28
	v_lshl_add_u64 v[20:21], v[92:93], 0, s[20:21]
	global_store_short_d16_hi v[20:21], v19, off
.LBB0_861:
	s_or_b64 exec, exec, s[48:49]
	v_pk_mul_f32 v[2:3], v[84:85], v[2:3]
	s_nop 0
	v_pk_fma_f32 v[2:3], v[18:19], v[26:27], v[2:3] op_sel_hi:[0,1,1]
	v_pk_fma_f32 v[84:85], v[94:95], v[10:11], v[2:3] op_sel_hi:[0,1,1]
	v_pk_mul_f32 v[2:3], v[86:87], v[4:5]
	s_waitcnt lgkmcnt(5)
	v_pk_fma_f32 v[78:79], v[84:85], v[78:79], 0 op_sel_hi:[1,1,0]
	v_pk_fma_f32 v[2:3], v[18:19], v[28:29], v[2:3] op_sel_hi:[0,1,1]
	v_pk_fma_f32 v[86:87], v[94:95], v[12:13], v[2:3] op_sel_hi:[0,1,1]
	v_pk_mul_f32 v[2:3], v[88:89], v[6:7]
	v_pk_fma_f32 v[70:71], v[84:85], v[70:71], 0 op_sel_hi:[1,1,0]
	v_pk_fma_f32 v[2:3], v[18:19], v[30:31], v[2:3] op_sel_hi:[0,1,1]
	v_pk_fma_f32 v[88:89], v[94:95], v[14:15], v[2:3] op_sel_hi:[0,1,1]
	v_pk_mul_f32 v[2:3], v[90:91], v[8:9]
	v_pk_fma_f32 v[78:79], v[86:87], v[80:81], v[78:79]
	v_pk_fma_f32 v[2:3], v[18:19], v[32:33], v[2:3] op_sel_hi:[0,1,1]
	v_pk_fma_f32 v[90:91], v[94:95], v[16:17], v[2:3] op_sel_hi:[0,1,1]
	ds_read_b128 v[22:25], v96 offset:3136
	ds_read_b128 v[18:21], v96 offset:3152
	ds_read_b128 v[2:5], v96 offset:3392
	ds_read_b128 v[6:9], v96 offset:3408
	ds_read_b128 v[10:13], v96 offset:3648
	ds_read_b128 v[14:17], v96 offset:3664
	ds_read_b128 v[34:37], v96 offset:3904
	ds_read_b128 v[38:41], v96 offset:3920
	ds_read_b128 v[26:29], v96 offset:4160
	ds_read_b128 v[30:33], v96 offset:4176
	v_pk_fma_f32 v[70:71], v[86:87], v[72:73], v[70:71]
	s_waitcnt lgkmcnt(14)
	v_pk_fma_f32 v[72:73], v[88:89], v[74:75], v[78:79]
	v_pk_fma_f32 v[66:67], v[88:89], v[66:67], v[70:71]
	v_mov_b32_e32 v95, s7
	ds_read_b32 v94, v103 offset:4416
	ds_read_b64 v[96:97], v95 offset:4672
	v_pk_fma_f32 v[70:71], v[90:91], v[76:77], v[72:73]
	v_pk_fma_f32 v[68:69], v[90:91], v[68:69], v[66:67]
	v_add_f32_e32 v66, v70, v71
	v_add_f32_e32 v67, v68, v69
	s_nop 0
	v_add_f32_dpp v66, v66, v66 quad_perm:[1,0,3,2] row_mask:0xf bank_mask:0xf bound_ctrl:1
	v_add_f32_dpp v67, v67, v67 quad_perm:[1,0,3,2] row_mask:0xf bank_mask:0xf bound_ctrl:1
	s_nop 0
	v_add_f32_dpp v66, v66, v66 quad_perm:[2,3,0,1] row_mask:0xf bank_mask:0xf bound_ctrl:1
	v_add_f32_dpp v68, v67, v67 quad_perm:[2,3,0,1] row_mask:0xf bank_mask:0xf bound_ctrl:1
	s_nop 0
	v_add_f32_dpp v66, v66, v66 row_half_mirror row_mask:0xf bank_mask:0xf bound_ctrl:1
	v_mov_b32_dpp v69, v68 row_half_mirror row_mask:0xf bank_mask:0xf bound_ctrl:1
	s_waitcnt lgkmcnt(13)
	v_mov_b32_e32 v67, v0
	s_waitcnt lgkmcnt(12)
	v_pk_mul_f32 v[70:71], v[98:99], v[66:67]
	v_add_f32_e32 v67, v68, v69
	v_add_f32_e32 v67, v70, v67
	s_add_i32 s20, s2, s46
	v_add_f32_e32 v67, v71, v67
	s_ashr_i32 s21, s20, 31
	v_bfe_u32 v68, v67, 16, 1
	s_lshl_b64 s[20:21], s[20:21], 9
	v_add3_u32 v67, v67, v68, s28
	v_lshl_add_u64 v[68:69], v[92:93], 0, s[20:21]
	global_store_short_d16_hi v[68:69], v67, off
	s_branch .LBB0_858

.LBB0_869:
	s_waitcnt lgkmcnt(0)
	v_mov_b32_e32 v95, v96
	v_add_u32_e32 v96, s6, v100
	ds_read_b128 v[70:73], v96 offset:26656
	ds_read_b128 v[66:69], v96 offset:26672
	ds_read_b128 v[50:53], v96 offset:26912
	ds_read_b128 v[46:49], v96 offset:26928
	ds_read_b128 v[54:57], v96 offset:27168
	ds_read_b128 v[42:45], v96 offset:27184
	ds_read_b128 v[78:81], v96 offset:27424
	ds_read_b128 v[74:77], v96 offset:27440
	ds_read_b128 v[62:65], v96 offset:27680
	ds_read_b128 v[58:61], v96 offset:27696
	v_pk_fma_f32 v[34:35], v[84:85], v[34:35], 0 op_sel_hi:[1,1,0]
	v_pk_fma_f32 v[22:23], v[84:85], v[22:23], 0 op_sel_hi:[1,1,0]
	v_pk_fma_f32 v[34:35], v[86:87], v[36:37], v[34:35]
	v_pk_fma_f32 v[22:23], v[86:87], v[24:25], v[22:23]
	v_add_u32_e32 v103, s6, v102
	v_mov_b32_e32 v98, s6
	v_pk_fma_f32 v[24:25], v[88:89], v[38:39], v[34:35]
	v_pk_fma_f32 v[18:19], v[88:89], v[18:19], v[22:23]
	ds_read_b32 v0, v103 offset:27936
	ds_read_b64 v[98:99], v98 offset:28192
	v_pk_fma_f32 v[22:23], v[90:91], v[40:41], v[24:25]
	v_pk_fma_f32 v[20:21], v[90:91], v[20:21], v[18:19]
	v_add_f32_e32 v18, v22, v23
	v_add_f32_e32 v19, v20, v21
	s_nop 0
	v_add_f32_dpp v18, v18, v18 quad_perm:[1,0,3,2] row_mask:0xf bank_mask:0xf bound_ctrl:1
	v_add_f32_dpp v19, v19, v19 quad_perm:[1,0,3,2] row_mask:0xf bank_mask:0xf bound_ctrl:1
	s_nop 0
	v_add_f32_dpp v18, v18, v18 quad_perm:[2,3,0,1] row_mask:0xf bank_mask:0xf bound_ctrl:1
	v_add_f32_dpp v19, v19, v19 quad_perm:[2,3,0,1] row_mask:0xf bank_mask:0xf bound_ctrl:1
	s_nop 0
	v_add_f32_dpp v18, v18, v18 row_half_mirror row_mask:0xf bank_mask:0xf bound_ctrl:1
	v_mov_b32_dpp v20, v19 row_half_mirror row_mask:0xf bank_mask:0xf bound_ctrl:1
	v_mov_b32_e32 v22, v97
	v_mov_b32_e32 v23, v18
	v_pk_mul_f32 v[22:23], v[22:23], v[94:95]
	v_add_f32_e32 v19, v19, v20
	v_add_f32_e32 v19, v23, v19
	v_add_f32_e32 v19, v22, v19
	s_ashr_i32 s19, s18, 31
	v_bfe_u32 v20, v19, 16, 1
	s_lshl_b64 s[10:11], s[18:19], 9
	v_add3_u32 v19, v19, v20, s28
	v_lshl_add_u64 v[20:21], v[92:93], 0, s[10:11]
	global_store_short_d16_hi v[20:21], v19, off
.LBB0_871:
	s_or_b64 exec, exec, s[46:47]
	v_pk_mul_f32 v[2:3], v[84:85], v[2:3]
	s_nop 0
	v_pk_fma_f32 v[2:3], v[18:19], v[26:27], v[2:3] op_sel_hi:[0,1,1]
	v_pk_fma_f32 v[84:85], v[94:95], v[10:11], v[2:3] op_sel_hi:[0,1,1]
	v_pk_mul_f32 v[2:3], v[86:87], v[4:5]
	s_waitcnt lgkmcnt(5)
	v_pk_fma_f32 v[78:79], v[84:85], v[78:79], 0 op_sel_hi:[1,1,0]
	v_pk_fma_f32 v[2:3], v[18:19], v[28:29], v[2:3] op_sel_hi:[0,1,1]
	v_pk_fma_f32 v[86:87], v[94:95], v[12:13], v[2:3] op_sel_hi:[0,1,1]
	v_pk_mul_f32 v[2:3], v[88:89], v[6:7]
	v_pk_fma_f32 v[70:71], v[84:85], v[70:71], 0 op_sel_hi:[1,1,0]
	v_pk_fma_f32 v[2:3], v[18:19], v[30:31], v[2:3] op_sel_hi:[0,1,1]
	v_pk_fma_f32 v[88:89], v[94:95], v[14:15], v[2:3] op_sel_hi:[0,1,1]
	v_pk_mul_f32 v[2:3], v[90:91], v[8:9]
	v_pk_fma_f32 v[78:79], v[86:87], v[80:81], v[78:79]
	v_pk_fma_f32 v[2:3], v[18:19], v[32:33], v[2:3] op_sel_hi:[0,1,1]
	v_pk_fma_f32 v[90:91], v[94:95], v[16:17], v[2:3] op_sel_hi:[0,1,1]
	ds_read_b128 v[22:25], v96 offset:28224
	ds_read_b128 v[18:21], v96 offset:28240
	ds_read_b128 v[2:5], v96 offset:28480
	ds_read_b128 v[6:9], v96 offset:28496
	ds_read_b128 v[10:13], v96 offset:28736
	ds_read_b128 v[14:17], v96 offset:28752
	ds_read_b128 v[34:37], v96 offset:28992
	ds_read_b128 v[38:41], v96 offset:29008
	ds_read_b128 v[26:29], v96 offset:29248
	ds_read_b128 v[30:33], v96 offset:29264
	v_pk_fma_f32 v[70:71], v[86:87], v[72:73], v[70:71]
	s_waitcnt lgkmcnt(14)
	v_pk_fma_f32 v[72:73], v[88:89], v[74:75], v[78:79]
	v_pk_fma_f32 v[66:67], v[88:89], v[66:67], v[70:71]
	v_mov_b32_e32 v95, s6
	ds_read_b32 v94, v103 offset:29504
	ds_read_b64 v[96:97], v95 offset:29760
	v_pk_fma_f32 v[70:71], v[90:91], v[76:77], v[72:73]
	v_pk_fma_f32 v[68:69], v[90:91], v[68:69], v[66:67]
	v_add_f32_e32 v66, v70, v71
	v_add_f32_e32 v67, v68, v69
	s_nop 0
	v_add_f32_dpp v66, v66, v66 quad_perm:[1,0,3,2] row_mask:0xf bank_mask:0xf bound_ctrl:1
	v_add_f32_dpp v67, v67, v67 quad_perm:[1,0,3,2] row_mask:0xf bank_mask:0xf bound_ctrl:1
	s_nop 0
	v_add_f32_dpp v66, v66, v66 quad_perm:[2,3,0,1] row_mask:0xf bank_mask:0xf bound_ctrl:1
	v_add_f32_dpp v68, v67, v67 quad_perm:[2,3,0,1] row_mask:0xf bank_mask:0xf bound_ctrl:1
	s_nop 0
	v_add_f32_dpp v66, v66, v66 row_half_mirror row_mask:0xf bank_mask:0xf bound_ctrl:1
	v_mov_b32_dpp v69, v68 row_half_mirror row_mask:0xf bank_mask:0xf bound_ctrl:1
	s_waitcnt lgkmcnt(13)
	v_mov_b32_e32 v67, v0
	s_waitcnt lgkmcnt(12)
	v_pk_mul_f32 v[70:71], v[98:99], v[66:67]
	v_add_f32_e32 v67, v68, v69
	v_add_f32_e32 v67, v70, v67
	s_add_i32 s10, s2, s18
	v_add_f32_e32 v67, v71, v67
	s_ashr_i32 s11, s10, 31
	v_bfe_u32 v68, v67, 16, 1
	s_lshl_b64 s[10:11], s[10:11], 9
	v_add3_u32 v67, v67, v68, s28
	v_lshl_add_u64 v[68:69], v[92:93], 0, s[10:11]
	global_store_short_d16_hi v[68:69], v67, off
	s_branch .LBB0_868

.LBB0_906:
	s_waitcnt lgkmcnt(5)
	v_pk_fma_f32 v[100:101], v[74:75], v[2:3], 0 op_sel_hi:[1,1,0]
	s_waitcnt lgkmcnt(0)
	v_mov_b32_e32 v37, v34
	v_add_u32_e32 v34, s7, v94
	v_pk_fma_f32 v[30:31], v[74:75], v[30:31], 0 op_sel_hi:[1,1,0]
	v_pk_fma_f32 v[100:101], v[78:79], v[4:5], v[100:101]
	ds_read_b128 v[66:69], v34 offset:800
	ds_read_b128 v[62:65], v34 offset:816
	ds_read_b128 v[58:61], v34 offset:832
	ds_read_b128 v[54:57], v34 offset:848
	ds_read_b128 v[50:53], v34 offset:1056
	ds_read_b128 v[46:49], v34 offset:1072
	ds_read_b128 v[42:45], v34 offset:1088
	ds_read_b128 v[38:41], v34 offset:1104
	v_pk_fma_f32 v[30:31], v[78:79], v[32:33], v[30:31]
	v_pk_fma_f32 v[32:33], v[80:81], v[6:7], v[100:101]
	v_pk_fma_f32 v[26:27], v[80:81], v[26:27], v[30:31]
	v_pk_fma_f32 v[30:31], v[82:83], v[8:9], v[32:33]
	v_pk_fma_f32 v[26:27], v[82:83], v[28:29], v[26:27]
	s_waitcnt lgkmcnt(9)
	v_pk_fma_f32 v[28:29], v[84:85], v[14:15], v[30:31]
	v_pk_fma_f32 v[22:23], v[84:85], v[22:23], v[26:27]
	v_pk_fma_f32 v[26:27], v[86:87], v[16:17], v[28:29]
	v_pk_fma_f32 v[22:23], v[86:87], v[24:25], v[22:23]
	s_waitcnt lgkmcnt(8)
	v_pk_fma_f32 v[24:25], v[88:89], v[10:11], v[26:27]
	v_add_u32_e32 v98, s7, v97
	v_mov_b32_e32 v70, s7
	v_pk_fma_f32 v[18:19], v[88:89], v[18:19], v[22:23]
	v_pk_fma_f32 v[22:23], v[90:91], v[12:13], v[24:25]
	ds_read_b32 v0, v98
	ds_read_b96 v[70:72], v70 offset:1568
	v_pk_fma_f32 v[18:19], v[90:91], v[20:21], v[18:19]
	v_add_f32_e32 v20, v22, v23
	v_add_f32_e32 v18, v18, v19
	s_nop 0
	v_add_f32_dpp v20, v20, v20 quad_perm:[1,0,3,2] row_mask:0xf bank_mask:0xf bound_ctrl:1
	v_add_f32_dpp v19, v18, v18 quad_perm:[1,0,3,2] row_mask:0xf bank_mask:0xf bound_ctrl:1
	s_nop 0
	v_add_f32_dpp v20, v20, v20 quad_perm:[2,3,0,1] row_mask:0xf bank_mask:0xf bound_ctrl:1
	v_fma_f32 v18, -v37, v20, v73
	v_mul_f32_e32 v18, v35, v18
	v_mov_b32_dpp v20, v19 quad_perm:[2,3,0,1] row_mask:0xf bank_mask:0xf bound_ctrl:1
	v_add_f32_e32 v19, v19, v20
	v_mul_f32_e32 v20, v37, v19
	v_pk_fma_f32 v[20:21], v[36:37], v[18:19], v[20:21] op_sel_hi:[1,1,0]
	s_ashr_i32 s19, s18, 31
	v_bfe_u32 v19, v20, 16, 1
	s_lshl_b64 s[20:21], s[18:19], 9
	v_add3_u32 v19, v20, v19, s28
	v_lshl_add_u64 v[20:21], v[92:93], 0, s[20:21]
	global_store_short_d16_hi v[20:21], v19, off
.LBB0_908:
	s_or_b64 exec, exec, s[46:47]
	v_pk_mul_f32 v[20:21], v[74:75], v[36:37] op_sel:[0,1]
	s_nop 0
	v_pk_fma_f32 v[74:75], v[2:3], v[18:19], v[20:21] op_sel_hi:[1,0,1]
	v_pk_mul_f32 v[2:3], v[78:79], v[36:37] op_sel:[0,1]
	s_waitcnt lgkmcnt(9)
	v_pk_fma_f32 v[66:67], v[74:75], v[66:67], 0 op_sel_hi:[1,1,0]
	v_pk_fma_f32 v[78:79], v[4:5], v[18:19], v[2:3] op_sel_hi:[1,0,1]
	v_pk_mul_f32 v[2:3], v[80:81], v[36:37] op_sel:[0,1]
	v_pk_fma_f32 v[66:67], v[78:79], v[68:69], v[66:67]
	v_pk_fma_f32 v[80:81], v[6:7], v[18:19], v[2:3] op_sel_hi:[1,0,1]
	v_pk_mul_f32 v[2:3], v[82:83], v[36:37] op_sel:[0,1]
	s_waitcnt lgkmcnt(8)
	v_pk_fma_f32 v[62:63], v[80:81], v[62:63], v[66:67]
	v_pk_fma_f32 v[82:83], v[8:9], v[18:19], v[2:3] op_sel_hi:[1,0,1]
	v_pk_mul_f32 v[2:3], v[84:85], v[36:37] op_sel:[0,1]
	v_pk_fma_f32 v[62:63], v[82:83], v[64:65], v[62:63]
	v_pk_fma_f32 v[84:85], v[14:15], v[18:19], v[2:3] op_sel_hi:[1,0,1]
	v_pk_mul_f32 v[2:3], v[86:87], v[36:37] op_sel:[0,1]
	s_waitcnt lgkmcnt(7)
	v_pk_fma_f32 v[58:59], v[84:85], v[58:59], v[62:63]
	v_pk_fma_f32 v[86:87], v[16:17], v[18:19], v[2:3] op_sel_hi:[1,0,1]
	v_pk_mul_f32 v[2:3], v[88:89], v[36:37] op_sel:[0,1]
	v_pk_fma_f32 v[58:59], v[86:87], v[60:61], v[58:59]
	v_pk_fma_f32 v[88:89], v[10:11], v[18:19], v[2:3] op_sel_hi:[1,0,1]
	v_pk_mul_f32 v[2:3], v[90:91], v[36:37] op_sel:[0,1]
	s_waitcnt lgkmcnt(6)
	v_pk_fma_f32 v[54:55], v[88:89], v[54:55], v[58:59]
	v_pk_fma_f32 v[90:91], v[12:13], v[18:19], v[2:3] op_sel_hi:[1,0,1]
	ds_read_b128 v[30:33], v34 offset:1600
	ds_read_b128 v[26:29], v34 offset:1616
	ds_read_b128 v[22:25], v34 offset:1632
	ds_read_b128 v[18:21], v34 offset:1648
	ds_read_b128 v[2:5], v34 offset:1856
	ds_read_b128 v[6:9], v34 offset:1872
	ds_read_b128 v[14:17], v34 offset:1888
	ds_read_b128 v[10:13], v34 offset:1904
	v_mov_b32_e32 v34, s7
	ds_read_b32 v73, v98 offset:800
	ds_read_b96 v[34:36], v34 offset:2368
	s_waitcnt lgkmcnt(14)
	v_pk_fma_f32 v[98:99], v[74:75], v[50:51], 0 op_sel_hi:[1,1,0]
	v_pk_fma_f32 v[54:55], v[90:91], v[56:57], v[54:55]
	v_pk_fma_f32 v[98:99], v[78:79], v[52:53], v[98:99]
	s_nop 0
	v_pk_fma_f32 v[68:69], v[80:81], v[46:47], v[98:99]
	s_nop 0
	v_pk_fma_f32 v[66:67], v[82:83], v[48:49], v[68:69]
	s_waitcnt lgkmcnt(13)
	v_pk_fma_f32 v[64:65], v[84:85], v[42:43], v[66:67]
	s_nop 0
	v_pk_fma_f32 v[62:63], v[86:87], v[44:45], v[64:65]
	s_waitcnt lgkmcnt(12)
	v_pk_fma_f32 v[60:61], v[88:89], v[38:39], v[62:63]
	s_nop 0
	v_pk_fma_f32 v[58:59], v[90:91], v[40:41], v[60:61]
	s_nop 0
	v_add_f32_e32 v37, v58, v59
	s_nop 1
	v_add_f32_dpp v37, v37, v37 quad_perm:[1,0,3,2] row_mask:0xf bank_mask:0xf bound_ctrl:1
	s_nop 1
	v_add_f32_dpp v56, v37, v37 quad_perm:[2,3,0,1] row_mask:0xf bank_mask:0xf bound_ctrl:1
	v_add_f32_e32 v37, v54, v55
	s_waitcnt lgkmcnt(10)
	v_fma_f32 v0, -v70, v56, v0
	v_mul_f32_e32 v0, v71, v0
	v_add_f32_dpp v37, v37, v37 quad_perm:[1,0,3,2] row_mask:0xf bank_mask:0xf bound_ctrl:1
	s_nop 1
	v_mov_b32_dpp v54, v37 quad_perm:[2,3,0,1] row_mask:0xf bank_mask:0xf bound_ctrl:1
	v_add_f32_e32 v54, v37, v54
	v_mov_b32_e32 v71, v72
	v_mov_b32_e32 v55, v0
	v_mul_f32_e32 v56, v72, v0
	s_add_i32 s20, s24, s18
	v_pk_fma_f32 v[54:55], v[70:71], v[54:55], v[56:57] op_sel_hi:[1,1,0]
	s_ashr_i32 s21, s20, 31
	v_bfe_u32 v37, v54, 16, 1
	s_lshl_b64 s[20:21], s[20:21], 9
	v_add3_u32 v37, v54, v37, s28
	v_lshl_add_u64 v[54:55], v[92:93], 0, s[20:21]
	global_store_short_d16_hi v[54:55], v37, off
	s_branch .LBB0_905

.LBB0_916:
	s_waitcnt lgkmcnt(5)
	v_pk_fma_f32 v[100:101], v[74:75], v[2:3], 0 op_sel_hi:[1,1,0]
	s_waitcnt lgkmcnt(0)
	v_mov_b32_e32 v37, v34
	v_add_u32_e32 v34, s7, v94
	v_pk_fma_f32 v[30:31], v[74:75], v[30:31], 0 op_sel_hi:[1,1,0]
	v_pk_fma_f32 v[100:101], v[78:79], v[4:5], v[100:101]
	ds_read_b128 v[66:69], v34
	ds_read_b128 v[62:65], v34 offset:16
	ds_read_b128 v[58:61], v34 offset:32
	ds_read_b128 v[54:57], v34 offset:48
	ds_read_b128 v[50:53], v34 offset:256
	ds_read_b128 v[46:49], v34 offset:272
	ds_read_b128 v[42:45], v34 offset:288
	ds_read_b128 v[38:41], v34 offset:304
	v_pk_fma_f32 v[30:31], v[78:79], v[32:33], v[30:31]
	v_pk_fma_f32 v[32:33], v[80:81], v[6:7], v[100:101]
	v_pk_fma_f32 v[26:27], v[80:81], v[26:27], v[30:31]
	v_pk_fma_f32 v[30:31], v[82:83], v[8:9], v[32:33]
	v_pk_fma_f32 v[26:27], v[82:83], v[28:29], v[26:27]
	s_waitcnt lgkmcnt(9)
	v_pk_fma_f32 v[28:29], v[84:85], v[14:15], v[30:31]
	v_pk_fma_f32 v[22:23], v[84:85], v[22:23], v[26:27]
	v_pk_fma_f32 v[26:27], v[86:87], v[16:17], v[28:29]
	v_pk_fma_f32 v[22:23], v[86:87], v[24:25], v[22:23]
	s_waitcnt lgkmcnt(8)
	v_pk_fma_f32 v[24:25], v[88:89], v[10:11], v[26:27]
	v_add_u32_e32 v98, s7, v96
	v_mov_b32_e32 v70, s7
	v_pk_fma_f32 v[18:19], v[88:89], v[18:19], v[22:23]
	v_pk_fma_f32 v[22:23], v[90:91], v[12:13], v[24:25]
	ds_read_b32 v0, v98 offset:512
	ds_read_b96 v[70:72], v70 offset:768
	v_pk_fma_f32 v[18:19], v[90:91], v[20:21], v[18:19]
	v_add_f32_e32 v20, v22, v23
	v_add_f32_e32 v18, v18, v19
	s_nop 0
	v_add_f32_dpp v20, v20, v20 quad_perm:[1,0,3,2] row_mask:0xf bank_mask:0xf bound_ctrl:1
	v_add_f32_dpp v19, v18, v18 quad_perm:[1,0,3,2] row_mask:0xf bank_mask:0xf bound_ctrl:1
	s_nop 0
	v_add_f32_dpp v20, v20, v20 quad_perm:[2,3,0,1] row_mask:0xf bank_mask:0xf bound_ctrl:1
	v_fma_f32 v18, -v37, v20, v73
	v_mul_f32_e32 v18, v35, v18
	v_mov_b32_dpp v20, v19 quad_perm:[2,3,0,1] row_mask:0xf bank_mask:0xf bound_ctrl:1
	v_add_f32_e32 v19, v19, v20
	v_mul_f32_e32 v20, v37, v19
	v_pk_fma_f32 v[20:21], v[36:37], v[18:19], v[20:21] op_sel_hi:[1,1,0]
	s_ashr_i32 s17, s16, 31
	v_bfe_u32 v19, v20, 16, 1
	s_lshl_b64 s[10:11], s[16:17], 9
	v_add3_u32 v19, v20, v19, s28
	v_lshl_add_u64 v[20:21], v[92:93], 0, s[10:11]
	global_store_short_d16_hi v[20:21], v19, off
.LBB0_918:
	s_or_b64 exec, exec, s[18:19]
	v_pk_mul_f32 v[20:21], v[74:75], v[36:37] op_sel:[0,1]
	s_nop 0
	v_pk_fma_f32 v[74:75], v[2:3], v[18:19], v[20:21] op_sel_hi:[1,0,1]
	v_pk_mul_f32 v[2:3], v[78:79], v[36:37] op_sel:[0,1]
	s_waitcnt lgkmcnt(9)
	v_pk_fma_f32 v[66:67], v[74:75], v[66:67], 0 op_sel_hi:[1,1,0]
	v_pk_fma_f32 v[78:79], v[4:5], v[18:19], v[2:3] op_sel_hi:[1,0,1]
	v_pk_mul_f32 v[2:3], v[80:81], v[36:37] op_sel:[0,1]
	v_pk_fma_f32 v[66:67], v[78:79], v[68:69], v[66:67]
	v_pk_fma_f32 v[80:81], v[6:7], v[18:19], v[2:3] op_sel_hi:[1,0,1]
	v_pk_mul_f32 v[2:3], v[82:83], v[36:37] op_sel:[0,1]
	s_waitcnt lgkmcnt(8)
	v_pk_fma_f32 v[62:63], v[80:81], v[62:63], v[66:67]
	v_pk_fma_f32 v[82:83], v[8:9], v[18:19], v[2:3] op_sel_hi:[1,0,1]
	v_pk_mul_f32 v[2:3], v[84:85], v[36:37] op_sel:[0,1]
	v_pk_fma_f32 v[62:63], v[82:83], v[64:65], v[62:63]
	v_pk_fma_f32 v[84:85], v[14:15], v[18:19], v[2:3] op_sel_hi:[1,0,1]
	v_pk_mul_f32 v[2:3], v[86:87], v[36:37] op_sel:[0,1]
	s_waitcnt lgkmcnt(7)
	v_pk_fma_f32 v[58:59], v[84:85], v[58:59], v[62:63]
	v_pk_fma_f32 v[86:87], v[16:17], v[18:19], v[2:3] op_sel_hi:[1,0,1]
	v_pk_mul_f32 v[2:3], v[88:89], v[36:37] op_sel:[0,1]
	v_pk_fma_f32 v[58:59], v[86:87], v[60:61], v[58:59]
	v_pk_fma_f32 v[88:89], v[10:11], v[18:19], v[2:3] op_sel_hi:[1,0,1]
	v_pk_mul_f32 v[2:3], v[90:91], v[36:37] op_sel:[0,1]
	s_waitcnt lgkmcnt(6)
	v_pk_fma_f32 v[54:55], v[88:89], v[54:55], v[58:59]
	v_pk_fma_f32 v[90:91], v[12:13], v[18:19], v[2:3] op_sel_hi:[1,0,1]
	ds_read_b128 v[30:33], v34 offset:800
	ds_read_b128 v[26:29], v34 offset:816
	ds_read_b128 v[22:25], v34 offset:832
	ds_read_b128 v[18:21], v34 offset:848
	ds_read_b128 v[2:5], v34 offset:1056
	ds_read_b128 v[6:9], v34 offset:1072
	ds_read_b128 v[14:17], v34 offset:1088
	ds_read_b128 v[10:13], v34 offset:1104
	v_mov_b32_e32 v34, s7
	ds_read_b32 v73, v98 offset:1312
	ds_read_b96 v[34:36], v34 offset:1568
	s_waitcnt lgkmcnt(14)
	v_pk_fma_f32 v[98:99], v[74:75], v[50:51], 0 op_sel_hi:[1,1,0]
	v_pk_fma_f32 v[54:55], v[90:91], v[56:57], v[54:55]
	v_pk_fma_f32 v[98:99], v[78:79], v[52:53], v[98:99]
	s_nop 0
	v_pk_fma_f32 v[68:69], v[80:81], v[46:47], v[98:99]
	s_nop 0
	v_pk_fma_f32 v[66:67], v[82:83], v[48:49], v[68:69]
	s_waitcnt lgkmcnt(13)
	v_pk_fma_f32 v[64:65], v[84:85], v[42:43], v[66:67]
	s_nop 0
	v_pk_fma_f32 v[62:63], v[86:87], v[44:45], v[64:65]
	s_waitcnt lgkmcnt(12)
	v_pk_fma_f32 v[60:61], v[88:89], v[38:39], v[62:63]
	s_nop 0
	v_pk_fma_f32 v[58:59], v[90:91], v[40:41], v[60:61]
	s_nop 0
	v_add_f32_e32 v37, v58, v59
	s_nop 1
	v_add_f32_dpp v37, v37, v37 quad_perm:[1,0,3,2] row_mask:0xf bank_mask:0xf bound_ctrl:1
	s_nop 1
	v_add_f32_dpp v56, v37, v37 quad_perm:[2,3,0,1] row_mask:0xf bank_mask:0xf bound_ctrl:1
	v_add_f32_e32 v37, v54, v55
	s_waitcnt lgkmcnt(10)
	v_fma_f32 v0, -v70, v56, v0
	v_mul_f32_e32 v0, v71, v0
	v_add_f32_dpp v37, v37, v37 quad_perm:[1,0,3,2] row_mask:0xf bank_mask:0xf bound_ctrl:1
	s_nop 1
	v_mov_b32_dpp v54, v37 quad_perm:[2,3,0,1] row_mask:0xf bank_mask:0xf bound_ctrl:1
	v_add_f32_e32 v54, v37, v54
	v_mov_b32_e32 v71, v72
	v_mov_b32_e32 v55, v0
	v_mul_f32_e32 v56, v72, v0
	s_add_i32 s10, s24, s16
	v_pk_fma_f32 v[54:55], v[70:71], v[54:55], v[56:57] op_sel_hi:[1,1,0]
	s_ashr_i32 s11, s10, 31
	v_bfe_u32 v37, v54, 16, 1
	s_lshl_b64 s[10:11], s[10:11], 9
	v_add3_u32 v37, v54, v37, s28
	v_lshl_add_u64 v[54:55], v[92:93], 0, s[10:11]
	global_store_short_d16_hi v[54:55], v37, off
	s_branch .LBB0_915
